# mlstm_scan: normaliser (NL) chunk scan done by 2 workgroups was a 128-step load-store-wait chain; loads now batched 16 steps per trip. m1: workgroups 0-7 (gate statistics) skip the conv share
# speedup vs baseline: 1.0094x; 1.0034x over previous
.LBB0_477:
	s_cmp_lt_i32 s2, 8
	s_cbranch_scc1 .LBB0_491
	s_ashr_i32 s3, s2, 31
	s_add_i32 s0, s2, -8
	s_ashr_i32 s1, s0, 31
	s_lshl_b64 s[0:1], s[0:1], 9
	v_ashrrev_i32_e32 v1, 31, v0
	v_lshl_add_u64 v[44:45], s[0:1], 0, v[0:1]
	s_mov_b64 s[0:1], 0x200000
	v_cmp_gt_u64_e32 vcc, s[0:1], v[44:45]
	s_and_saveexec_b64 s[4:5], vcc
	s_cbranch_execz .LBB0_490
	v_lshlrev_b32_e32 v0, 3, v0
	v_and_b32_e32 v46, 0x3f8, v0
	v_mov_b32_e32 v49, 0
	v_lshlrev_b32_e32 v48, 1, v46
	v_lshl_add_u64 v[50:51], s[24:25], 0, v[48:49]
	v_lshl_add_u64 v[40:41], s[22:23], 0, v[48:49]
	v_lshlrev_b32_e32 v48, 2, v46
	v_lshl_add_u64 v[16:17], s[18:19], 0, v[48:49]
	s_mov_b64 s[0:1], 0x3000
	s_movk_i32 s3, 0x3000
	v_lshl_add_u64 v[8:9], v[16:17], 0, s[0:1]
	v_add_co_u32_e32 v10, vcc, s3, v16
	s_mov_b64 s[0:1], 0x2000
	s_nop 0
	v_addc_co_u32_e32 v11, vcc, 0, v17, vcc
	v_lshl_add_u64 v[18:19], v[16:17], 0, s[0:1]
	s_movk_i32 s0, 0x2000
	v_add_co_u32_e32 v20, vcc, s0, v16
	s_movk_i32 s22, 0x1000
	s_nop 0
	v_addc_co_u32_e32 v21, vcc, 0, v17, vcc
	s_mov_b64 s[0:1], 0x1000
	v_add_co_u32_e32 v52, vcc, s22, v16
	global_load_dwordx4 v[0:3], v[10:11], off
	global_load_dwordx4 v[4:7], v[8:9], off offset:16
	s_nop 0
	global_load_dwordx4 v[8:11], v[20:21], off
	global_load_dwordx4 v[12:15], v[18:19], off offset:16
	v_lshl_add_u64 v[42:43], v[16:17], 0, s[0:1]
	v_addc_co_u32_e32 v53, vcc, 0, v17, vcc
	global_load_dwordx4 v[16:19], v48, s[18:19] offset:16
	global_load_dwordx4 v[20:23], v48, s[18:19]
	global_load_dwordx4 v[24:27], v48, s[20:21] offset:16
	global_load_dwordx4 v[28:31], v48, s[20:21]
	global_load_dwordx4 v[32:35], v[52:53], off
	global_load_dwordx4 v[36:39], v[42:43], off offset:16
	s_movk_i32 s13, 0x200
	s_ashr_i32 s35, s34, 31
	v_mov_b32_e32 v42, 0x3db504f3
	s_add_i32 s10, s34, -8
	s_ashr_i32 s11, s10, 31
	s_lshl_b64 s[10:11], s[10:11], 9
	v_cmp_gt_u32_e32 vcc, s13, v46
	s_movk_i32 s0, 0x1ff
	s_mov_b64 s[14:15], 0x3ab00000
	s_add_u32 s12, s31, 0x29a00000
	v_cndmask_b32_e32 v56, 1.0, v42, vcc
	s_mov_b64 s[6:7], 0
	s_movk_i32 s18, 0x1800
	s_mov_b32 s19, 0xffff0000
	s_movk_i32 s20, 0x7fff
	s_mov_b64 s[8:9], 0x1fffff
	v_mov_b32_e32 v53, 0xffffb800
	v_mov_b32_e32 v55, 0xffffd000
	v_cmp_lt_u32_e64 s[0:1], s0, v46
	s_addc_u32 s13, s30, 0
	v_mov_b32_e32 v57, v56
	v_lshl_add_u64 v[58:59], v[40:41], 0, s[14:15]
	s_waitcnt vmcnt(0)
	v_mov_b32_e32 v60, v1
	v_mov_b32_e32 v61, v3
	v_mov_b32_e32 v1, v2
	v_mov_b32_e32 v2, v5
	v_mov_b32_e32 v3, v7
	v_mov_b32_e32 v5, v6
	v_mov_b32_e32 v7, 0xffffe800
	s_branch .LBB0_480

.LBB0_708:
	v_lshl_add_u64 v[6:7], v[0:1], 0, s[0:1]
	v_add_co_u32_e32 v6, vcc, 0x3cb83000, v6
	s_mov_b64 s[98:99], 0x1000
	s_nop 0
	v_addc_co_u32_e32 v7, vcc, 0, v7, vcc
	v_lshl_add_u64 v[8:9], v[6:7], 0, s[98:99]
	global_load_dword v100, v[6:7], off
	global_load_dword v101, v[6:7], off offset:512
	global_load_dword v102, v[6:7], off offset:1024
	global_load_dword v103, v[6:7], off offset:1536
	global_load_dword v104, v[6:7], off offset:2048
	global_load_dword v105, v[6:7], off offset:2560
	global_load_dword v106, v[6:7], off offset:3072
	global_load_dword v107, v[6:7], off offset:3584
	global_load_dword v108, v[8:9], off
	global_load_dword v109, v[8:9], off offset:512
	global_load_dword v110, v[8:9], off offset:1024
	global_load_dword v111, v[8:9], off offset:1536
	global_load_dword v112, v[8:9], off offset:2048
	global_load_dword v113, v[8:9], off offset:2560
	global_load_dword v114, v[8:9], off offset:3072
	global_load_dword v115, v[8:9], off offset:3584
	global_load_dword v120, v[2:3], off offset:-4
	global_load_dword v121, v[2:3], off
	global_load_dword v122, v[2:3], off offset:4
	global_load_dword v123, v[2:3], off offset:8
	global_load_dword v124, v[2:3], off offset:12
	global_load_dword v125, v[2:3], off offset:16
	global_load_dword v126, v[2:3], off offset:20
	global_load_dword v127, v[2:3], off offset:24
	global_load_dword v128, v[2:3], off offset:28
	global_load_dword v129, v[2:3], off offset:32
	global_load_dword v130, v[2:3], off offset:36
	global_load_dword v131, v[2:3], off offset:40
	global_load_dword v132, v[2:3], off offset:44
	global_load_dword v133, v[2:3], off offset:48
	global_load_dword v134, v[2:3], off offset:52
	global_load_dword v135, v[2:3], off offset:56
	s_waitcnt vmcnt(0)
	global_store_dword v[6:7], v4, off
	v_fmac_f32_e32 v100, v4, v120
	global_store_dword v[6:7], v100, off offset:512
	v_fmac_f32_e32 v101, v100, v121
	global_store_dword v[6:7], v101, off offset:1024
	v_fmac_f32_e32 v102, v101, v122
	global_store_dword v[6:7], v102, off offset:1536
	v_fmac_f32_e32 v103, v102, v123
	global_store_dword v[6:7], v103, off offset:2048
	v_fmac_f32_e32 v104, v103, v124
	global_store_dword v[6:7], v104, off offset:2560
	v_fmac_f32_e32 v105, v104, v125
	global_store_dword v[6:7], v105, off offset:3072
	v_fmac_f32_e32 v106, v105, v126
	global_store_dword v[6:7], v106, off offset:3584
	v_fmac_f32_e32 v107, v106, v127
	global_store_dword v[8:9], v107, off
	v_fmac_f32_e32 v108, v107, v128
	global_store_dword v[8:9], v108, off offset:512
	v_fmac_f32_e32 v109, v108, v129
	global_store_dword v[8:9], v109, off offset:1024
	v_fmac_f32_e32 v110, v109, v130
	global_store_dword v[8:9], v110, off offset:1536
	v_fmac_f32_e32 v111, v110, v131
	global_store_dword v[8:9], v111, off offset:2048
	v_fmac_f32_e32 v112, v111, v132
	global_store_dword v[8:9], v112, off offset:2560
	v_fmac_f32_e32 v113, v112, v133
	global_store_dword v[8:9], v113, off offset:3072
	v_fmac_f32_e32 v114, v113, v134
	global_store_dword v[8:9], v114, off offset:3584
	v_fmac_f32_e32 v115, v114, v135
	v_mov_b32_e32 v4, v115
	s_add_u32 s0, s0, 0x2000
	s_addc_u32 s1, s1, 0
	v_lshl_add_u64 v[2:3], v[2:3], 0, 64
	s_cmp_lg_u32 s0, 0x10000
	s_cbranch_scc1 .LBB0_708
